# SwiGLU epilogue math rewritten with packed f32 multiply/add, two quads per batch, no padding after transcendentals
# speedup vs baseline: 1.0066x; 1.0031x over previous
; __device__ __forceinline__ unsigned cvt_pk_bf16(float lo, float hi) { unsigned r; asm volatile("v_cvt_pk_bf16_f32 %0, %1, %2" : "=v"(r) : "v"(lo), "v"(hi)); return r; }
; #define GAS __attribute__((address_space(1)))
; __device__ __forceinline__ float fast_exp2(float x) { return __builtin_amdgcn_exp2f(x); }
; __device__ __forceinline__ float fast_rcp(float x) { return __builtin_amdgcn_rcpf(x); }
; __device__ __forceinline__ float sigmoidf_(float x) { return fast_rcp(1.0f + fast_exp2(-x * LOG2E)); }
; __device__ __forceinline__ float siluf_(float x) { return x * sigmoidf_(x); }
;     __device__ __forceinline__ bool operator()(AccT& acc, const Unit& u, int wr, int wc, int fr, int fq) const {
;     ...
;             for (int mp = 0; mp < 2; ++mp) { bf16* rowp = act + (size_t)(row0 + ai * 128 + mp * 32) * DFF + col0;
; #pragma unroll
;                 for (int bj = 0; bj < 2; ++bj) { unsigned pk[2][2];
; #pragma unroll
;                     for (int k = 0; k < 2; ++k) { const f32x4 g = acc[ai][bj][2 * mp + k][0], up = acc[ai][bj][2 * mp + k][1];
;                         pk[k][0] = pg8::cvt_pk_bf16(siluf_(g[0]) * up[0], siluf_(g[1]) * up[1]); pk[k][1] = pg8::cvt_pk_bf16(siluf_(g[2]) * up[2], siluf_(g[3]) * up[3]); }
;                     const auto sx = __builtin_amdgcn_permlane16_swap(pk[0][0], pk[1][0], false, false), sy = __builtin_amdgcn_permlane16_swap(pk[0][1], pk[1][1], false, false);
;                     *(GAS v4u*)(rowp + bj * 64) = (v4u){sx[0], sy[0], sx[1], sy[1]}; } }
.LBB0_164:
	s_add_u32 s100, s68, 0x40080
	s_addc_u32 s101, s13, 0
	v_lshl_add_u64 v[194:195], s[100:101], 0, v[220:221]
	s_add_i32 m0, s41, 0xc000
	s_nop 0
	global_load_lds_dwordx4 v[194:195], off
	v_lshl_add_u64 v[194:195], s[100:101], 0, v[218:219]
	s_add_i32 m0, s41, 0xe000
	s_nop 0
	global_load_lds_dwordx4 v[194:195], off
	s_mov_b32 s100, 0xbfb8aa3b
	s_mov_b32 s101, 0xbfb8aa3b
	s_mov_b32 s11, s39
	v_mov_b32_e32 v130, v1
	s_mov_b32 s13, s56
	v_mov_b32_e32 v131, v245
	s_lshl_b32 s19, s19, 7
	s_lshl_b32 s13, s13, 4
	s_lshl_b32 s18, s18, 8
	s_lshl_b32 s11, s11, 6
	v_lshlrev_b32_e32 v132, 4, v131
	s_add_i32 s13, s13, s19
	v_lshlrev_b32_e32 v131, 2, v131
	v_and_b32_e32 v133, 16, v132
	v_and_or_b32 v132, v131, 8, s13
	s_add_i32 s11, s11, s18
	v_add3_u32 v136, s11, v130, v133
	v_ashrrev_i32_e32 v133, 31, v132
	v_mov_b64_e32 v[130:131], s[6:7]
	s_movk_i32 s11, 0x1600
	v_mad_i64_i32 v[134:135], s[18:19], v136, s11, v[130:131]
	v_lshlrev_b64 v[132:133], 1, v[132:133]
	v_lshl_add_u64 v[134:135], v[134:135], 0, v[132:133]
	s_andn2_b64 vcc, exec, s[4:5]
	v_pk_mul_f32 v[138:139], v[126:127], s[100:101]
	v_pk_mul_f32 v[140:141], v[128:129], s[100:101]
	v_pk_mul_f32 v[142:143], v[118:119], s[100:101]
	v_pk_mul_f32 v[144:145], v[120:121], s[100:101]
	v_exp_f32_e32 v138, v138
	v_exp_f32_e32 v139, v139
	v_exp_f32_e32 v140, v140
	v_exp_f32_e32 v141, v141
	v_exp_f32_e32 v142, v142
	v_exp_f32_e32 v143, v143
	v_exp_f32_e32 v144, v144
	v_exp_f32_e32 v145, v145
	v_pk_add_f32 v[138:139], v[138:139], 1.0 op_sel_hi:[1,0]
	v_pk_add_f32 v[140:141], v[140:141], 1.0 op_sel_hi:[1,0]
	v_pk_add_f32 v[142:143], v[142:143], 1.0 op_sel_hi:[1,0]
	v_pk_add_f32 v[144:145], v[144:145], 1.0 op_sel_hi:[1,0]
	v_rcp_f32_e32 v138, v138
	v_rcp_f32_e32 v139, v139
	v_rcp_f32_e32 v140, v140
	v_rcp_f32_e32 v141, v141
	v_rcp_f32_e32 v142, v142
	v_rcp_f32_e32 v143, v143
	v_rcp_f32_e32 v144, v144
	v_rcp_f32_e32 v145, v145
	v_pk_mul_f32 v[126:127], v[126:127], v[138:139]
	v_pk_mul_f32 v[128:129], v[128:129], v[140:141]
	v_pk_mul_f32 v[118:119], v[118:119], v[142:143]
	v_pk_mul_f32 v[120:121], v[120:121], v[144:145]
	v_pk_mul_f32 v[122:123], v[122:123], v[126:127]
	v_pk_mul_f32 v[124:125], v[124:125], v[128:129]
	v_pk_mul_f32 v[114:115], v[114:115], v[118:119]
	v_pk_mul_f32 v[116:117], v[116:117], v[120:121]
	v_cvt_pk_bf16_f32 v122, v122, v123
	v_cvt_pk_bf16_f32 v123, v124, v125
	v_cvt_pk_bf16_f32 v124, v114, v115
	v_cvt_pk_bf16_f32 v125, v116, v117
	s_nop 1
	v_permlane16_swap_b32_e32 v122, v124
	v_permlane16_swap_b32_e32 v123, v125
	global_store_dwordx4 v[134:135], v[122:125], off
	v_pk_mul_f32 v[138:139], v[110:111], s[100:101]
	v_pk_mul_f32 v[140:141], v[112:113], s[100:101]
	v_pk_mul_f32 v[142:143], v[102:103], s[100:101]
	v_pk_mul_f32 v[144:145], v[104:105], s[100:101]
	v_exp_f32_e32 v138, v138
	v_exp_f32_e32 v139, v139
	v_exp_f32_e32 v140, v140
	v_exp_f32_e32 v141, v141
	v_exp_f32_e32 v142, v142
	v_exp_f32_e32 v143, v143
	v_exp_f32_e32 v144, v144
	v_exp_f32_e32 v145, v145
	v_pk_add_f32 v[138:139], v[138:139], 1.0 op_sel_hi:[1,0]
	v_pk_add_f32 v[140:141], v[140:141], 1.0 op_sel_hi:[1,0]
	v_pk_add_f32 v[142:143], v[142:143], 1.0 op_sel_hi:[1,0]
	v_pk_add_f32 v[144:145], v[144:145], 1.0 op_sel_hi:[1,0]
	v_rcp_f32_e32 v138, v138
	v_rcp_f32_e32 v139, v139
	v_rcp_f32_e32 v140, v140
	v_rcp_f32_e32 v141, v141
	v_rcp_f32_e32 v142, v142
	v_rcp_f32_e32 v143, v143
	v_rcp_f32_e32 v144, v144
	v_rcp_f32_e32 v145, v145
	v_pk_mul_f32 v[110:111], v[110:111], v[138:139]
	v_pk_mul_f32 v[112:113], v[112:113], v[140:141]
	v_pk_mul_f32 v[102:103], v[102:103], v[142:143]
	v_pk_mul_f32 v[104:105], v[104:105], v[144:145]
	v_pk_mul_f32 v[106:107], v[106:107], v[110:111]
	v_pk_mul_f32 v[108:109], v[108:109], v[112:113]
	v_pk_mul_f32 v[98:99], v[98:99], v[102:103]
	v_pk_mul_f32 v[100:101], v[100:101], v[104:105]
	v_cvt_pk_bf16_f32 v106, v106, v107
	v_cvt_pk_bf16_f32 v107, v108, v109
	v_cvt_pk_bf16_f32 v108, v98, v99
	v_cvt_pk_bf16_f32 v109, v100, v101
	s_nop 1
	v_permlane16_swap_b32_e32 v106, v108
	v_permlane16_swap_b32_e32 v107, v109
	global_store_dwordx4 v[134:135], v[106:109], off offset:128
	v_add_u32_e32 v98, 32, v136
	v_mad_i64_i32 v[98:99], s[18:19], v98, s11, v[130:131]
	v_lshl_add_u64 v[98:99], v[98:99], 0, v[132:133]
	v_pk_mul_f32 v[138:139], v[94:95], s[100:101]
	v_pk_mul_f32 v[140:141], v[96:97], s[100:101]
	v_pk_mul_f32 v[142:143], v[86:87], s[100:101]
	v_pk_mul_f32 v[144:145], v[88:89], s[100:101]
	v_exp_f32_e32 v138, v138
	v_exp_f32_e32 v139, v139
	v_exp_f32_e32 v140, v140
	v_exp_f32_e32 v141, v141
	v_exp_f32_e32 v142, v142
	v_exp_f32_e32 v143, v143
	v_exp_f32_e32 v144, v144
	v_exp_f32_e32 v145, v145
	v_pk_add_f32 v[138:139], v[138:139], 1.0 op_sel_hi:[1,0]
	v_pk_add_f32 v[140:141], v[140:141], 1.0 op_sel_hi:[1,0]
	v_pk_add_f32 v[142:143], v[142:143], 1.0 op_sel_hi:[1,0]
	v_pk_add_f32 v[144:145], v[144:145], 1.0 op_sel_hi:[1,0]
	v_rcp_f32_e32 v138, v138
	v_rcp_f32_e32 v139, v139
	v_rcp_f32_e32 v140, v140
	v_rcp_f32_e32 v141, v141
	v_rcp_f32_e32 v142, v142
	v_rcp_f32_e32 v143, v143
	v_rcp_f32_e32 v144, v144
	v_rcp_f32_e32 v145, v145
	v_pk_mul_f32 v[94:95], v[94:95], v[138:139]
	v_pk_mul_f32 v[96:97], v[96:97], v[140:141]
	v_pk_mul_f32 v[86:87], v[86:87], v[142:143]
	v_pk_mul_f32 v[88:89], v[88:89], v[144:145]
	v_pk_mul_f32 v[90:91], v[90:91], v[94:95]
	v_pk_mul_f32 v[92:93], v[92:93], v[96:97]
	v_pk_mul_f32 v[82:83], v[82:83], v[86:87]
	v_pk_mul_f32 v[84:85], v[84:85], v[88:89]
	v_cvt_pk_bf16_f32 v90, v90, v91
	v_cvt_pk_bf16_f32 v91, v92, v93
	v_cvt_pk_bf16_f32 v92, v82, v83
	v_cvt_pk_bf16_f32 v93, v84, v85
	s_nop 1
	v_permlane16_swap_b32_e32 v90, v92
	v_permlane16_swap_b32_e32 v91, v93
; __device__ __forceinline__ unsigned cvt_pk_bf16(float lo, float hi) { unsigned r; asm volatile("v_cvt_pk_bf16_f32 %0, %1, %2" : "=v"(r) : "v"(lo), "v"(hi)); return r; }
; #define GAS __attribute__((address_space(1)))
; __device__ __forceinline__ float fast_exp2(float x) { return __builtin_amdgcn_exp2f(x); }
; __device__ __forceinline__ float fast_rcp(float x) { return __builtin_amdgcn_rcpf(x); }
; __device__ __forceinline__ float sigmoidf_(float x) { return fast_rcp(1.0f + fast_exp2(-x * LOG2E)); }
; __device__ __forceinline__ float siluf_(float x) { return x * sigmoidf_(x); }
;     __device__ __forceinline__ bool operator()(AccT& acc, const Unit& u, int wr, int wc, int fr, int fq) const {
;     ...
;             for (int mp = 0; mp < 2; ++mp) { bf16* rowp = act + (size_t)(row0 + ai * 128 + mp * 32) * DFF + col0;
; #pragma unroll
;                 for (int bj = 0; bj < 2; ++bj) { unsigned pk[2][2];
; #pragma unroll
;                     for (int k = 0; k < 2; ++k) { const f32x4 g = acc[ai][bj][2 * mp + k][0], up = acc[ai][bj][2 * mp + k][1];
;                         pk[k][0] = pg8::cvt_pk_bf16(siluf_(g[0]) * up[0], siluf_(g[1]) * up[1]); pk[k][1] = pg8::cvt_pk_bf16(siluf_(g[2]) * up[2], siluf_(g[3]) * up[3]); }
;                     const auto sx = __builtin_amdgcn_permlane16_swap(pk[0][0], pk[1][0], false, false), sy = __builtin_amdgcn_permlane16_swap(pk[0][1], pk[1][1], false, false);
;                     *(GAS v4u*)(rowp + bj * 64) = (v4u){sx[0], sy[0], sx[1], sy[1]}; } }
	global_store_dwordx4 v[98:99], v[90:93], off
	v_pk_mul_f32 v[138:139], v[78:79], s[100:101]
	v_pk_mul_f32 v[140:141], v[80:81], s[100:101]
	v_pk_mul_f32 v[142:143], v[70:71], s[100:101]
	v_pk_mul_f32 v[144:145], v[72:73], s[100:101]
	v_exp_f32_e32 v138, v138
	v_exp_f32_e32 v139, v139
	v_exp_f32_e32 v140, v140
	v_exp_f32_e32 v141, v141
	v_exp_f32_e32 v142, v142
	v_exp_f32_e32 v143, v143
	v_exp_f32_e32 v144, v144
	v_exp_f32_e32 v145, v145
	v_pk_add_f32 v[138:139], v[138:139], 1.0 op_sel_hi:[1,0]
	v_pk_add_f32 v[140:141], v[140:141], 1.0 op_sel_hi:[1,0]
	v_pk_add_f32 v[142:143], v[142:143], 1.0 op_sel_hi:[1,0]
	v_pk_add_f32 v[144:145], v[144:145], 1.0 op_sel_hi:[1,0]
	v_rcp_f32_e32 v138, v138
	v_rcp_f32_e32 v139, v139
	v_rcp_f32_e32 v140, v140
	v_rcp_f32_e32 v141, v141
	v_rcp_f32_e32 v142, v142
	v_rcp_f32_e32 v143, v143
	v_rcp_f32_e32 v144, v144
	v_rcp_f32_e32 v145, v145
	v_pk_mul_f32 v[78:79], v[78:79], v[138:139]
	v_pk_mul_f32 v[80:81], v[80:81], v[140:141]
	v_pk_mul_f32 v[70:71], v[70:71], v[142:143]
	v_pk_mul_f32 v[72:73], v[72:73], v[144:145]
	v_pk_mul_f32 v[74:75], v[74:75], v[78:79]
	v_pk_mul_f32 v[76:77], v[76:77], v[80:81]
	v_pk_mul_f32 v[66:67], v[66:67], v[70:71]
	v_pk_mul_f32 v[68:69], v[68:69], v[72:73]
	v_cvt_pk_bf16_f32 v74, v74, v75
	v_cvt_pk_bf16_f32 v75, v76, v77
	v_cvt_pk_bf16_f32 v76, v66, v67
	v_cvt_pk_bf16_f32 v77, v68, v69
	s_nop 1
	v_permlane16_swap_b32_e32 v74, v76
	v_permlane16_swap_b32_e32 v75, v77
	global_store_dwordx4 v[98:99], v[74:77], off offset:128
	v_add_u32_e32 v66, 0x80, v136
	v_mad_i64_i32 v[66:67], s[18:19], v66, s11, v[130:131]
	v_lshl_add_u64 v[66:67], v[66:67], 0, v[132:133]
	v_pk_mul_f32 v[138:139], v[62:63], s[100:101]
	v_pk_mul_f32 v[140:141], v[64:65], s[100:101]
	v_pk_mul_f32 v[142:143], v[54:55], s[100:101]
	v_pk_mul_f32 v[144:145], v[56:57], s[100:101]
	v_exp_f32_e32 v138, v138
	v_exp_f32_e32 v139, v139
	v_exp_f32_e32 v140, v140
	v_exp_f32_e32 v141, v141
	v_exp_f32_e32 v142, v142
	v_exp_f32_e32 v143, v143
	v_exp_f32_e32 v144, v144
	v_exp_f32_e32 v145, v145
	v_pk_add_f32 v[138:139], v[138:139], 1.0 op_sel_hi:[1,0]
	v_pk_add_f32 v[140:141], v[140:141], 1.0 op_sel_hi:[1,0]
	v_pk_add_f32 v[142:143], v[142:143], 1.0 op_sel_hi:[1,0]
	v_pk_add_f32 v[144:145], v[144:145], 1.0 op_sel_hi:[1,0]
	v_rcp_f32_e32 v138, v138
	v_rcp_f32_e32 v139, v139
	v_rcp_f32_e32 v140, v140
	v_rcp_f32_e32 v141, v141
	v_rcp_f32_e32 v142, v142
	v_rcp_f32_e32 v143, v143
	v_rcp_f32_e32 v144, v144
	v_rcp_f32_e32 v145, v145
	v_pk_mul_f32 v[62:63], v[62:63], v[138:139]
	v_pk_mul_f32 v[64:65], v[64:65], v[140:141]
	v_pk_mul_f32 v[54:55], v[54:55], v[142:143]
	v_pk_mul_f32 v[56:57], v[56:57], v[144:145]
	v_pk_mul_f32 v[58:59], v[58:59], v[62:63]
	v_pk_mul_f32 v[60:61], v[60:61], v[64:65]
	v_pk_mul_f32 v[50:51], v[50:51], v[54:55]
	v_pk_mul_f32 v[52:53], v[52:53], v[56:57]
	v_cvt_pk_bf16_f32 v58, v58, v59
	v_cvt_pk_bf16_f32 v59, v60, v61
	v_cvt_pk_bf16_f32 v60, v50, v51
	v_cvt_pk_bf16_f32 v61, v52, v53
	s_nop 1
	v_permlane16_swap_b32_e32 v58, v60
	v_permlane16_swap_b32_e32 v59, v61
	global_store_dwordx4 v[66:67], v[58:61], off
	v_pk_mul_f32 v[138:139], v[46:47], s[100:101]
	v_pk_mul_f32 v[140:141], v[48:49], s[100:101]
	v_pk_mul_f32 v[142:143], v[38:39], s[100:101]
	v_pk_mul_f32 v[144:145], v[40:41], s[100:101]
	v_exp_f32_e32 v138, v138
	v_exp_f32_e32 v139, v139
	v_exp_f32_e32 v140, v140
	v_exp_f32_e32 v141, v141
	v_exp_f32_e32 v142, v142
	v_exp_f32_e32 v143, v143
	v_exp_f32_e32 v144, v144
	v_exp_f32_e32 v145, v145
	v_pk_add_f32 v[138:139], v[138:139], 1.0 op_sel_hi:[1,0]
	v_pk_add_f32 v[140:141], v[140:141], 1.0 op_sel_hi:[1,0]
	v_pk_add_f32 v[142:143], v[142:143], 1.0 op_sel_hi:[1,0]
	v_pk_add_f32 v[144:145], v[144:145], 1.0 op_sel_hi:[1,0]
	v_rcp_f32_e32 v138, v138
	v_rcp_f32_e32 v139, v139
	v_rcp_f32_e32 v140, v140
	v_rcp_f32_e32 v141, v141
	v_rcp_f32_e32 v142, v142
; __device__ __forceinline__ unsigned cvt_pk_bf16(float lo, float hi) { unsigned r; asm volatile("v_cvt_pk_bf16_f32 %0, %1, %2" : "=v"(r) : "v"(lo), "v"(hi)); return r; }
; #define GAS __attribute__((address_space(1)))
; __device__ __forceinline__ float fast_exp2(float x) { return __builtin_amdgcn_exp2f(x); }
; __device__ __forceinline__ float fast_rcp(float x) { return __builtin_amdgcn_rcpf(x); }
; __device__ __forceinline__ float sigmoidf_(float x) { return fast_rcp(1.0f + fast_exp2(-x * LOG2E)); }
; __device__ __forceinline__ float siluf_(float x) { return x * sigmoidf_(x); }
;     __device__ __forceinline__ bool operator()(AccT& acc, const Unit& u, int wr, int wc, int fr, int fq) const {
;     ...
;             for (int mp = 0; mp < 2; ++mp) { bf16* rowp = act + (size_t)(row0 + ai * 128 + mp * 32) * DFF + col0;
; #pragma unroll
;                 for (int bj = 0; bj < 2; ++bj) { unsigned pk[2][2];
; #pragma unroll
;                     for (int k = 0; k < 2; ++k) { const f32x4 g = acc[ai][bj][2 * mp + k][0], up = acc[ai][bj][2 * mp + k][1];
;                         pk[k][0] = pg8::cvt_pk_bf16(siluf_(g[0]) * up[0], siluf_(g[1]) * up[1]); pk[k][1] = pg8::cvt_pk_bf16(siluf_(g[2]) * up[2], siluf_(g[3]) * up[3]); }
;                     const auto sx = __builtin_amdgcn_permlane16_swap(pk[0][0], pk[1][0], false, false), sy = __builtin_amdgcn_permlane16_swap(pk[0][1], pk[1][1], false, false);
;                     *(GAS v4u*)(rowp + bj * 64) = (v4u){sx[0], sy[0], sx[1], sy[1]}; } }
	v_rcp_f32_e32 v143, v143
	v_rcp_f32_e32 v144, v144
	v_rcp_f32_e32 v145, v145
	v_pk_mul_f32 v[46:47], v[46:47], v[138:139]
	v_pk_mul_f32 v[48:49], v[48:49], v[140:141]
	v_pk_mul_f32 v[38:39], v[38:39], v[142:143]
	v_pk_mul_f32 v[40:41], v[40:41], v[144:145]
	v_pk_mul_f32 v[42:43], v[42:43], v[46:47]
	v_pk_mul_f32 v[44:45], v[44:45], v[48:49]
	v_pk_mul_f32 v[34:35], v[34:35], v[38:39]
	v_pk_mul_f32 v[36:37], v[36:37], v[40:41]
	v_cvt_pk_bf16_f32 v42, v42, v43
	v_cvt_pk_bf16_f32 v43, v44, v45
	v_cvt_pk_bf16_f32 v44, v34, v35
	v_cvt_pk_bf16_f32 v45, v36, v37
	s_nop 1
	v_permlane16_swap_b32_e32 v42, v44
	v_permlane16_swap_b32_e32 v43, v45
	global_store_dwordx4 v[66:67], v[42:45], off offset:128
	v_add_u32_e32 v34, 0xa0, v136
	v_mad_i64_i32 v[34:35], s[18:19], v34, s11, v[130:131]
	v_lshl_add_u64 v[34:35], v[34:35], 0, v[132:133]
	s_mov_b64 s[18:19], -1
	v_pk_mul_f32 v[138:139], v[30:31], s[100:101]
	v_pk_mul_f32 v[140:141], v[32:33], s[100:101]
	v_pk_mul_f32 v[142:143], v[22:23], s[100:101]
	v_pk_mul_f32 v[144:145], v[24:25], s[100:101]
	v_exp_f32_e32 v138, v138
	v_exp_f32_e32 v139, v139
	v_exp_f32_e32 v140, v140
	v_exp_f32_e32 v141, v141
	v_exp_f32_e32 v142, v142
	v_exp_f32_e32 v143, v143
	v_exp_f32_e32 v144, v144
	v_exp_f32_e32 v145, v145
	v_pk_add_f32 v[138:139], v[138:139], 1.0 op_sel_hi:[1,0]
	v_pk_add_f32 v[140:141], v[140:141], 1.0 op_sel_hi:[1,0]
	v_pk_add_f32 v[142:143], v[142:143], 1.0 op_sel_hi:[1,0]
	v_pk_add_f32 v[144:145], v[144:145], 1.0 op_sel_hi:[1,0]
	v_rcp_f32_e32 v138, v138
	v_rcp_f32_e32 v139, v139
	v_rcp_f32_e32 v140, v140
	v_rcp_f32_e32 v141, v141
	v_rcp_f32_e32 v142, v142
	v_rcp_f32_e32 v143, v143
	v_rcp_f32_e32 v144, v144
	v_rcp_f32_e32 v145, v145
	v_pk_mul_f32 v[30:31], v[30:31], v[138:139]
	v_pk_mul_f32 v[32:33], v[32:33], v[140:141]
	v_pk_mul_f32 v[22:23], v[22:23], v[142:143]
	v_pk_mul_f32 v[24:25], v[24:25], v[144:145]
	v_pk_mul_f32 v[26:27], v[26:27], v[30:31]
	v_pk_mul_f32 v[28:29], v[28:29], v[32:33]
	v_pk_mul_f32 v[18:19], v[18:19], v[22:23]
	v_pk_mul_f32 v[20:21], v[20:21], v[24:25]
	v_cvt_pk_bf16_f32 v26, v26, v27
	v_cvt_pk_bf16_f32 v27, v28, v29
	v_cvt_pk_bf16_f32 v28, v18, v19
	v_cvt_pk_bf16_f32 v29, v20, v21
	s_nop 1
	v_permlane16_swap_b32_e32 v26, v28
	v_permlane16_swap_b32_e32 v27, v29
	global_store_dwordx4 v[34:35], v[26:29], off
	v_pk_mul_f32 v[138:139], v[14:15], s[100:101]
	v_pk_mul_f32 v[140:141], v[16:17], s[100:101]
	v_pk_mul_f32 v[142:143], v[6:7], s[100:101]
	v_pk_mul_f32 v[144:145], v[8:9], s[100:101]
	v_exp_f32_e32 v138, v138
	v_exp_f32_e32 v139, v139
	v_exp_f32_e32 v140, v140
	v_exp_f32_e32 v141, v141
	v_exp_f32_e32 v142, v142
	v_exp_f32_e32 v143, v143
	v_exp_f32_e32 v144, v144
	v_exp_f32_e32 v145, v145
	v_pk_add_f32 v[138:139], v[138:139], 1.0 op_sel_hi:[1,0]
	v_pk_add_f32 v[140:141], v[140:141], 1.0 op_sel_hi:[1,0]
	v_pk_add_f32 v[142:143], v[142:143], 1.0 op_sel_hi:[1,0]
	v_pk_add_f32 v[144:145], v[144:145], 1.0 op_sel_hi:[1,0]
	v_rcp_f32_e32 v138, v138
	v_rcp_f32_e32 v139, v139
	v_rcp_f32_e32 v140, v140
	v_rcp_f32_e32 v141, v141
	v_rcp_f32_e32 v142, v142
	v_rcp_f32_e32 v143, v143
	v_rcp_f32_e32 v144, v144
	v_rcp_f32_e32 v145, v145
	v_pk_mul_f32 v[14:15], v[14:15], v[138:139]
	v_pk_mul_f32 v[16:17], v[16:17], v[140:141]
	v_pk_mul_f32 v[6:7], v[6:7], v[142:143]
	v_pk_mul_f32 v[8:9], v[8:9], v[144:145]
	v_pk_mul_f32 v[10:11], v[10:11], v[14:15]
	v_pk_mul_f32 v[12:13], v[12:13], v[16:17]
	v_pk_mul_f32 v[2:3], v[2:3], v[6:7]
	v_pk_mul_f32 v[4:5], v[4:5], v[8:9]
	v_cvt_pk_bf16_f32 v10, v10, v11
	v_cvt_pk_bf16_f32 v11, v12, v13
	v_cvt_pk_bf16_f32 v12, v2, v3
	v_cvt_pk_bf16_f32 v13, v4, v5
	s_nop 1
	v_permlane16_swap_b32_e32 v10, v12
	v_permlane16_swap_b32_e32 v11, v13
	global_store_dwordx4 v[34:35], v[10:13], off offset:128
	s_cbranch_vccnz .LBB0_149
	s_andn2_b64 vcc, exec, s[2:3]
	s_cbranch_vccnz .LBB0_148
	s_barrier
	s_branch .LBB0_148

; __device__ __forceinline__ unsigned cvt_pk_bf16(float lo, float hi) { unsigned r; asm volatile("v_cvt_pk_bf16_f32 %0, %1, %2" : "=v"(r) : "v"(lo), "v"(hi)); return r; }
; #define PG8_STAGE(bufoff, gbase, voff) do { _Pragma("unroll") for (int _i = 0; _i < 2; ++_i) \
;         __builtin_amdgcn_global_load_lds((const unsigned*)((const char*)(gbase) + (voff)[_i]), (PG8_LAS unsigned*)(lds + (bufoff) + ldsw + _i * 8192), 16, 0, 0); } while (0)
; #define PG8_LDA(dst, b, h) do { _Pragma("unroll") for (int m = 0; m < 4; ++m) _Pragma("unroll") for (int k = 0; k < 2; ++k) dst[m][k] = *(const PG8_LAS bf16x8*)(lds + PG8_SA(b, h) + aoff + m * 2048 + k * 1024); } while (0)
; #define GAS __attribute__((address_space(1)))
; __device__ __forceinline__ float siluf_(float x) { return x * sigmoidf_(x); }
; template <class Epi, class Sched, bool ALIGN_EPI = false, bool SP2 = false>
; __device__ __forceinline__ void gemm_phase(PG8_LAS unsigned char* lds, const Gemm g, const Sched& S, const Epi& E, const int wave_id) {
;     ...
;             PG8_LDA(At, 1, 1); PG8_STAGE(PG8_SB(1, 0), b3, voffB); PG8_STAGE(PG8_SB(1, 1), b3 + hstep, voffB); PG8_STAGE(PG8_SA(1, 0), a3, voffA);
;     __device__ __forceinline__ bool operator()(AccT& acc, const Unit& u, int wr, int wc, int fr, int fq) const {
;     ...
;             for (int mp = 0; mp < 2; ++mp) { bf16* rowp = act + (size_t)(row0 + ai * 128 + mp * 32) * DFF + col0;
; #pragma unroll
;                 for (int bj = 0; bj < 2; ++bj) { unsigned pk[2][2];
; #pragma unroll
;                     for (int k = 0; k < 2; ++k) { const f32x4 g = acc[ai][bj][2 * mp + k][0], up = acc[ai][bj][2 * mp + k][1];
;                         pk[k][0] = pg8::cvt_pk_bf16(siluf_(g[0]) * up[0], siluf_(g[1]) * up[1]); pk[k][1] = pg8::cvt_pk_bf16(siluf_(g[2]) * up[2], siluf_(g[3]) * up[3]); }
;                     const auto sx = __builtin_amdgcn_permlane16_swap(pk[0][0], pk[1][0], false, false), sy = __builtin_amdgcn_permlane16_swap(pk[0][1], pk[1][1], false, false);
;                     *(GAS v4u*)(rowp + bj * 64) = (v4u){sx[0], sy[0], sx[1], sy[1]}; } }
.LBB0_1959:
	s_add_u32 s100, s68, 0x40080
	s_addc_u32 s101, s13, 0
	v_lshl_add_u64 v[194:195], s[100:101], 0, v[220:221]
	s_add_i32 m0, s41, 0xc000
	s_nop 0
	global_load_lds_dwordx4 v[194:195], off
	v_lshl_add_u64 v[194:195], s[100:101], 0, v[218:219]
	s_add_i32 m0, s41, 0xe000
	s_nop 0
	global_load_lds_dwordx4 v[194:195], off
	s_mov_b32 s100, 0xbfb8aa3b
	s_mov_b32 s101, 0xbfb8aa3b
	s_mov_b32 s11, s56
	v_mov_b32_e32 v130, v245
	s_mov_b32 s13, s38
	v_mov_b32_e32 v131, v1
	s_lshl_b32 s19, s19, 7
	s_lshl_b32 s11, s11, 4
	s_lshl_b32 s18, s18, 8
	s_lshl_b32 s13, s13, 6
	v_lshlrev_b32_e32 v132, 4, v130
	s_add_i32 s11, s11, s19
	v_lshlrev_b32_e32 v130, 2, v130
	v_and_b32_e32 v133, 16, v132
	v_and_or_b32 v132, v130, 8, s11
	s_add_i32 s13, s13, s18
	v_add3_u32 v136, s13, v131, v133
	v_ashrrev_i32_e32 v133, 31, v132
	v_mov_b64_e32 v[130:131], s[4:5]
	s_movk_i32 s11, 0x1600
	v_mad_i64_i32 v[134:135], s[18:19], v136, s11, v[130:131]
	v_lshlrev_b64 v[132:133], 1, v[132:133]
	v_lshl_add_u64 v[134:135], v[134:135], 0, v[132:133]
	s_andn2_b64 vcc, exec, s[6:7]
	v_pk_mul_f32 v[138:139], v[126:127], s[100:101]
	v_pk_mul_f32 v[140:141], v[128:129], s[100:101]
	v_pk_mul_f32 v[142:143], v[118:119], s[100:101]
	v_pk_mul_f32 v[144:145], v[120:121], s[100:101]
	v_exp_f32_e32 v138, v138
	v_exp_f32_e32 v139, v139
	v_exp_f32_e32 v140, v140
	v_exp_f32_e32 v141, v141
	v_exp_f32_e32 v142, v142
	v_exp_f32_e32 v143, v143
	v_exp_f32_e32 v144, v144
	v_exp_f32_e32 v145, v145
	v_pk_add_f32 v[138:139], v[138:139], 1.0 op_sel_hi:[1,0]
	v_pk_add_f32 v[140:141], v[140:141], 1.0 op_sel_hi:[1,0]
	v_pk_add_f32 v[142:143], v[142:143], 1.0 op_sel_hi:[1,0]
	v_pk_add_f32 v[144:145], v[144:145], 1.0 op_sel_hi:[1,0]
	v_rcp_f32_e32 v138, v138
	v_rcp_f32_e32 v139, v139
	v_rcp_f32_e32 v140, v140
	v_rcp_f32_e32 v141, v141
	v_rcp_f32_e32 v142, v142
	v_rcp_f32_e32 v143, v143
	v_rcp_f32_e32 v144, v144
	v_rcp_f32_e32 v145, v145
	v_pk_mul_f32 v[126:127], v[126:127], v[138:139]
	v_pk_mul_f32 v[128:129], v[128:129], v[140:141]
	v_pk_mul_f32 v[118:119], v[118:119], v[142:143]
	v_pk_mul_f32 v[120:121], v[120:121], v[144:145]
	v_pk_mul_f32 v[122:123], v[122:123], v[126:127]
	v_pk_mul_f32 v[124:125], v[124:125], v[128:129]
	v_pk_mul_f32 v[114:115], v[114:115], v[118:119]
	v_pk_mul_f32 v[116:117], v[116:117], v[120:121]
	v_cvt_pk_bf16_f32 v122, v122, v123
	v_cvt_pk_bf16_f32 v123, v124, v125
	v_cvt_pk_bf16_f32 v124, v114, v115
	v_cvt_pk_bf16_f32 v125, v116, v117
	s_nop 1
	v_permlane16_swap_b32_e32 v122, v124
	v_permlane16_swap_b32_e32 v123, v125
	global_store_dwordx4 v[134:135], v[122:125], off
	v_pk_mul_f32 v[138:139], v[110:111], s[100:101]
	v_pk_mul_f32 v[140:141], v[112:113], s[100:101]
	v_pk_mul_f32 v[142:143], v[102:103], s[100:101]
	v_pk_mul_f32 v[144:145], v[104:105], s[100:101]
	v_exp_f32_e32 v138, v138
	v_exp_f32_e32 v139, v139
	v_exp_f32_e32 v140, v140
	v_exp_f32_e32 v141, v141
	v_exp_f32_e32 v142, v142
	v_exp_f32_e32 v143, v143
	v_exp_f32_e32 v144, v144
	v_exp_f32_e32 v145, v145
	v_pk_add_f32 v[138:139], v[138:139], 1.0 op_sel_hi:[1,0]
	v_pk_add_f32 v[140:141], v[140:141], 1.0 op_sel_hi:[1,0]
	v_pk_add_f32 v[142:143], v[142:143], 1.0 op_sel_hi:[1,0]
	v_pk_add_f32 v[144:145], v[144:145], 1.0 op_sel_hi:[1,0]
	v_rcp_f32_e32 v138, v138
	v_rcp_f32_e32 v139, v139
	v_rcp_f32_e32 v140, v140
	v_rcp_f32_e32 v141, v141
	v_rcp_f32_e32 v142, v142
	v_rcp_f32_e32 v143, v143
	v_rcp_f32_e32 v144, v144
	v_rcp_f32_e32 v145, v145
	v_pk_mul_f32 v[110:111], v[110:111], v[138:139]
	v_pk_mul_f32 v[112:113], v[112:113], v[140:141]
	v_pk_mul_f32 v[102:103], v[102:103], v[142:143]
	v_pk_mul_f32 v[104:105], v[104:105], v[144:145]
	v_pk_mul_f32 v[106:107], v[106:107], v[110:111]
	v_pk_mul_f32 v[108:109], v[108:109], v[112:113]
	v_pk_mul_f32 v[98:99], v[98:99], v[102:103]
	v_pk_mul_f32 v[100:101], v[100:101], v[104:105]
	v_cvt_pk_bf16_f32 v106, v106, v107
	v_cvt_pk_bf16_f32 v107, v108, v109
	v_cvt_pk_bf16_f32 v108, v98, v99
	v_cvt_pk_bf16_f32 v109, v100, v101
	s_nop 1
	v_permlane16_swap_b32_e32 v106, v108
	v_permlane16_swap_b32_e32 v107, v109
	global_store_dwordx4 v[134:135], v[106:109], off offset:128
	v_add_u32_e32 v98, 32, v136
	v_mad_i64_i32 v[98:99], s[18:19], v98, s11, v[130:131]
	v_lshl_add_u64 v[98:99], v[98:99], 0, v[132:133]
	v_pk_mul_f32 v[138:139], v[94:95], s[100:101]
	v_pk_mul_f32 v[140:141], v[96:97], s[100:101]
	v_pk_mul_f32 v[142:143], v[86:87], s[100:101]
	v_pk_mul_f32 v[144:145], v[88:89], s[100:101]
	v_exp_f32_e32 v138, v138
	v_exp_f32_e32 v139, v139
	v_exp_f32_e32 v140, v140
	v_exp_f32_e32 v141, v141
	v_exp_f32_e32 v142, v142
	v_exp_f32_e32 v143, v143
	v_exp_f32_e32 v144, v144
	v_exp_f32_e32 v145, v145
	v_pk_add_f32 v[138:139], v[138:139], 1.0 op_sel_hi:[1,0]
	v_pk_add_f32 v[140:141], v[140:141], 1.0 op_sel_hi:[1,0]
	v_pk_add_f32 v[142:143], v[142:143], 1.0 op_sel_hi:[1,0]
	v_pk_add_f32 v[144:145], v[144:145], 1.0 op_sel_hi:[1,0]
	v_rcp_f32_e32 v138, v138
	v_rcp_f32_e32 v139, v139
	v_rcp_f32_e32 v140, v140
	v_rcp_f32_e32 v141, v141
	v_rcp_f32_e32 v142, v142
	v_rcp_f32_e32 v143, v143
	v_rcp_f32_e32 v144, v144
	v_rcp_f32_e32 v145, v145
	v_pk_mul_f32 v[94:95], v[94:95], v[138:139]
	v_pk_mul_f32 v[96:97], v[96:97], v[140:141]
	v_pk_mul_f32 v[86:87], v[86:87], v[142:143]
	v_pk_mul_f32 v[88:89], v[88:89], v[144:145]
	v_pk_mul_f32 v[90:91], v[90:91], v[94:95]
	v_pk_mul_f32 v[92:93], v[92:93], v[96:97]
	v_pk_mul_f32 v[82:83], v[82:83], v[86:87]
	v_pk_mul_f32 v[84:85], v[84:85], v[88:89]
	v_cvt_pk_bf16_f32 v90, v90, v91
	v_cvt_pk_bf16_f32 v91, v92, v93
	v_cvt_pk_bf16_f32 v92, v82, v83
	v_cvt_pk_bf16_f32 v93, v84, v85
	s_nop 1
	v_permlane16_swap_b32_e32 v90, v92
	v_permlane16_swap_b32_e32 v91, v93
; __device__ __forceinline__ unsigned cvt_pk_bf16(float lo, float hi) { unsigned r; asm volatile("v_cvt_pk_bf16_f32 %0, %1, %2" : "=v"(r) : "v"(lo), "v"(hi)); return r; }
; #define GAS __attribute__((address_space(1)))
; __device__ __forceinline__ float siluf_(float x) { return x * sigmoidf_(x); }
;     __device__ __forceinline__ bool operator()(AccT& acc, const Unit& u, int wr, int wc, int fr, int fq) const {
;     ...
;             for (int mp = 0; mp < 2; ++mp) { bf16* rowp = act + (size_t)(row0 + ai * 128 + mp * 32) * DFF + col0;
; #pragma unroll
;                 for (int bj = 0; bj < 2; ++bj) { unsigned pk[2][2];
; #pragma unroll
;                     for (int k = 0; k < 2; ++k) { const f32x4 g = acc[ai][bj][2 * mp + k][0], up = acc[ai][bj][2 * mp + k][1];
;                         pk[k][0] = pg8::cvt_pk_bf16(siluf_(g[0]) * up[0], siluf_(g[1]) * up[1]); pk[k][1] = pg8::cvt_pk_bf16(siluf_(g[2]) * up[2], siluf_(g[3]) * up[3]); }
;                     const auto sx = __builtin_amdgcn_permlane16_swap(pk[0][0], pk[1][0], false, false), sy = __builtin_amdgcn_permlane16_swap(pk[0][1], pk[1][1], false, false);
;                     *(GAS v4u*)(rowp + bj * 64) = (v4u){sx[0], sy[0], sx[1], sy[1]}; } }
	global_store_dwordx4 v[98:99], v[90:93], off
	v_pk_mul_f32 v[138:139], v[78:79], s[100:101]
	v_pk_mul_f32 v[140:141], v[80:81], s[100:101]
	v_pk_mul_f32 v[142:143], v[70:71], s[100:101]
	v_pk_mul_f32 v[144:145], v[72:73], s[100:101]
	v_exp_f32_e32 v138, v138
	v_exp_f32_e32 v139, v139
	v_exp_f32_e32 v140, v140
	v_exp_f32_e32 v141, v141
	v_exp_f32_e32 v142, v142
	v_exp_f32_e32 v143, v143
	v_exp_f32_e32 v144, v144
	v_exp_f32_e32 v145, v145
	v_pk_add_f32 v[138:139], v[138:139], 1.0 op_sel_hi:[1,0]
	v_pk_add_f32 v[140:141], v[140:141], 1.0 op_sel_hi:[1,0]
	v_pk_add_f32 v[142:143], v[142:143], 1.0 op_sel_hi:[1,0]
	v_pk_add_f32 v[144:145], v[144:145], 1.0 op_sel_hi:[1,0]
	v_rcp_f32_e32 v138, v138
	v_rcp_f32_e32 v139, v139
	v_rcp_f32_e32 v140, v140
	v_rcp_f32_e32 v141, v141
	v_rcp_f32_e32 v142, v142
	v_rcp_f32_e32 v143, v143
	v_rcp_f32_e32 v144, v144
	v_rcp_f32_e32 v145, v145
	v_pk_mul_f32 v[78:79], v[78:79], v[138:139]
	v_pk_mul_f32 v[80:81], v[80:81], v[140:141]
	v_pk_mul_f32 v[70:71], v[70:71], v[142:143]
	v_pk_mul_f32 v[72:73], v[72:73], v[144:145]
	v_pk_mul_f32 v[74:75], v[74:75], v[78:79]
	v_pk_mul_f32 v[76:77], v[76:77], v[80:81]
	v_pk_mul_f32 v[66:67], v[66:67], v[70:71]
	v_pk_mul_f32 v[68:69], v[68:69], v[72:73]
	v_cvt_pk_bf16_f32 v74, v74, v75
	v_cvt_pk_bf16_f32 v75, v76, v77
	v_cvt_pk_bf16_f32 v76, v66, v67
	v_cvt_pk_bf16_f32 v77, v68, v69
	s_nop 1
	v_permlane16_swap_b32_e32 v74, v76
	v_permlane16_swap_b32_e32 v75, v77
	global_store_dwordx4 v[98:99], v[74:77], off offset:128
	v_add_u32_e32 v66, 0x80, v136
	v_mad_i64_i32 v[66:67], s[18:19], v66, s11, v[130:131]
	v_lshl_add_u64 v[66:67], v[66:67], 0, v[132:133]
	v_pk_mul_f32 v[138:139], v[62:63], s[100:101]
	v_pk_mul_f32 v[140:141], v[64:65], s[100:101]
	v_pk_mul_f32 v[142:143], v[54:55], s[100:101]
	v_pk_mul_f32 v[144:145], v[56:57], s[100:101]
	v_exp_f32_e32 v138, v138
	v_exp_f32_e32 v139, v139
	v_exp_f32_e32 v140, v140
	v_exp_f32_e32 v141, v141
	v_exp_f32_e32 v142, v142
	v_exp_f32_e32 v143, v143
	v_exp_f32_e32 v144, v144
	v_exp_f32_e32 v145, v145
	v_pk_add_f32 v[138:139], v[138:139], 1.0 op_sel_hi:[1,0]
	v_pk_add_f32 v[140:141], v[140:141], 1.0 op_sel_hi:[1,0]
	v_pk_add_f32 v[142:143], v[142:143], 1.0 op_sel_hi:[1,0]
	v_pk_add_f32 v[144:145], v[144:145], 1.0 op_sel_hi:[1,0]
	v_rcp_f32_e32 v138, v138
	v_rcp_f32_e32 v139, v139
	v_rcp_f32_e32 v140, v140
	v_rcp_f32_e32 v141, v141
	v_rcp_f32_e32 v142, v142
	v_rcp_f32_e32 v143, v143
	v_rcp_f32_e32 v144, v144
	v_rcp_f32_e32 v145, v145
	v_pk_mul_f32 v[62:63], v[62:63], v[138:139]
	v_pk_mul_f32 v[64:65], v[64:65], v[140:141]
	v_pk_mul_f32 v[54:55], v[54:55], v[142:143]
	v_pk_mul_f32 v[56:57], v[56:57], v[144:145]
	v_pk_mul_f32 v[58:59], v[58:59], v[62:63]
	v_pk_mul_f32 v[60:61], v[60:61], v[64:65]
	v_pk_mul_f32 v[50:51], v[50:51], v[54:55]
	v_pk_mul_f32 v[52:53], v[52:53], v[56:57]
	v_cvt_pk_bf16_f32 v58, v58, v59
	v_cvt_pk_bf16_f32 v59, v60, v61
	v_cvt_pk_bf16_f32 v60, v50, v51
	v_cvt_pk_bf16_f32 v61, v52, v53
	s_nop 1
	v_permlane16_swap_b32_e32 v58, v60
	v_permlane16_swap_b32_e32 v59, v61
	global_store_dwordx4 v[66:67], v[58:61], off
	v_pk_mul_f32 v[138:139], v[46:47], s[100:101]
	v_pk_mul_f32 v[140:141], v[48:49], s[100:101]
	v_pk_mul_f32 v[142:143], v[38:39], s[100:101]
	v_pk_mul_f32 v[144:145], v[40:41], s[100:101]
	v_exp_f32_e32 v138, v138
	v_exp_f32_e32 v139, v139
	v_exp_f32_e32 v140, v140
	v_exp_f32_e32 v141, v141
	v_exp_f32_e32 v142, v142
	v_exp_f32_e32 v143, v143
	v_exp_f32_e32 v144, v144
	v_exp_f32_e32 v145, v145
	v_pk_add_f32 v[138:139], v[138:139], 1.0 op_sel_hi:[1,0]
	v_pk_add_f32 v[140:141], v[140:141], 1.0 op_sel_hi:[1,0]
	v_pk_add_f32 v[142:143], v[142:143], 1.0 op_sel_hi:[1,0]
	v_pk_add_f32 v[144:145], v[144:145], 1.0 op_sel_hi:[1,0]
	v_rcp_f32_e32 v138, v138
	v_rcp_f32_e32 v139, v139
	v_rcp_f32_e32 v140, v140
	v_rcp_f32_e32 v141, v141
	v_rcp_f32_e32 v142, v142
; __device__ __forceinline__ unsigned cvt_pk_bf16(float lo, float hi) { unsigned r; asm volatile("v_cvt_pk_bf16_f32 %0, %1, %2" : "=v"(r) : "v"(lo), "v"(hi)); return r; }
; #define PG8_BAR __builtin_amdgcn_s_barrier()
; #define GAS __attribute__((address_space(1)))
; __device__ __forceinline__ float siluf_(float x) { return x * sigmoidf_(x); }
; template <class Epi, class Sched, bool ALIGN_EPI = false, bool SP2 = false>
; __device__ __forceinline__ void gemm_phase(PG8_LAS unsigned char* lds, const Gemm g, const Sched& S, const Epi& E, const int wave_id) {
;     ...
;         if (!has_next) break;
;         if (!keep_acc) {
; #pragma unroll
;         for (int a = 0; a < 2; ++a)
; #pragma unroll
;             for (int b = 0; b < 2; ++b)
; #pragma unroll
;                 for (int m = 0; m < 4; ++m)
; #pragma unroll
;                     for (int n = 0; n < 2; ++n) acc[a][b][m][n] = (f32x4){0.f, 0.f, 0.f, 0.f};
;         }
;         cur = nxt; cA = nA; cB = nB; ++ui;
;         if constexpr (ALIGN_EPI) { if (wr == 1) PG8_BAR; }
;     __device__ __forceinline__ bool operator()(AccT& acc, const Unit& u, int wr, int wc, int fr, int fq) const {
;     ...
;             for (int mp = 0; mp < 2; ++mp) { bf16* rowp = act + (size_t)(row0 + ai * 128 + mp * 32) * DFF + col0;
; #pragma unroll
;                 for (int bj = 0; bj < 2; ++bj) { unsigned pk[2][2];
; #pragma unroll
;                     for (int k = 0; k < 2; ++k) { const f32x4 g = acc[ai][bj][2 * mp + k][0], up = acc[ai][bj][2 * mp + k][1];
;                         pk[k][0] = pg8::cvt_pk_bf16(siluf_(g[0]) * up[0], siluf_(g[1]) * up[1]); pk[k][1] = pg8::cvt_pk_bf16(siluf_(g[2]) * up[2], siluf_(g[3]) * up[3]); }
;                     const auto sx = __builtin_amdgcn_permlane16_swap(pk[0][0], pk[1][0], false, false), sy = __builtin_amdgcn_permlane16_swap(pk[0][1], pk[1][1], false, false);
;                     *(GAS v4u*)(rowp + bj * 64) = (v4u){sx[0], sy[0], sx[1], sy[1]}; } }
	v_rcp_f32_e32 v143, v143
	v_rcp_f32_e32 v144, v144
	v_rcp_f32_e32 v145, v145
	v_pk_mul_f32 v[46:47], v[46:47], v[138:139]
	v_pk_mul_f32 v[48:49], v[48:49], v[140:141]
	v_pk_mul_f32 v[38:39], v[38:39], v[142:143]
	v_pk_mul_f32 v[40:41], v[40:41], v[144:145]
	v_pk_mul_f32 v[42:43], v[42:43], v[46:47]
	v_pk_mul_f32 v[44:45], v[44:45], v[48:49]
	v_pk_mul_f32 v[34:35], v[34:35], v[38:39]
	v_pk_mul_f32 v[36:37], v[36:37], v[40:41]
	v_cvt_pk_bf16_f32 v42, v42, v43
	v_cvt_pk_bf16_f32 v43, v44, v45
	v_cvt_pk_bf16_f32 v44, v34, v35
	v_cvt_pk_bf16_f32 v45, v36, v37
	s_nop 1
	v_permlane16_swap_b32_e32 v42, v44
	v_permlane16_swap_b32_e32 v43, v45
	global_store_dwordx4 v[66:67], v[42:45], off offset:128
	v_add_u32_e32 v34, 0xa0, v136
	v_mad_i64_i32 v[34:35], s[18:19], v34, s11, v[130:131]
	v_lshl_add_u64 v[34:35], v[34:35], 0, v[132:133]
	s_mov_b64 s[18:19], -1
	v_pk_mul_f32 v[138:139], v[30:31], s[100:101]
	v_pk_mul_f32 v[140:141], v[32:33], s[100:101]
	v_pk_mul_f32 v[142:143], v[22:23], s[100:101]
	v_pk_mul_f32 v[144:145], v[24:25], s[100:101]
	v_exp_f32_e32 v138, v138
	v_exp_f32_e32 v139, v139
	v_exp_f32_e32 v140, v140
	v_exp_f32_e32 v141, v141
	v_exp_f32_e32 v142, v142
	v_exp_f32_e32 v143, v143
	v_exp_f32_e32 v144, v144
	v_exp_f32_e32 v145, v145
	v_pk_add_f32 v[138:139], v[138:139], 1.0 op_sel_hi:[1,0]
	v_pk_add_f32 v[140:141], v[140:141], 1.0 op_sel_hi:[1,0]
	v_pk_add_f32 v[142:143], v[142:143], 1.0 op_sel_hi:[1,0]
	v_pk_add_f32 v[144:145], v[144:145], 1.0 op_sel_hi:[1,0]
	v_rcp_f32_e32 v138, v138
	v_rcp_f32_e32 v139, v139
	v_rcp_f32_e32 v140, v140
	v_rcp_f32_e32 v141, v141
	v_rcp_f32_e32 v142, v142
	v_rcp_f32_e32 v143, v143
	v_rcp_f32_e32 v144, v144
	v_rcp_f32_e32 v145, v145
	v_pk_mul_f32 v[30:31], v[30:31], v[138:139]
	v_pk_mul_f32 v[32:33], v[32:33], v[140:141]
	v_pk_mul_f32 v[22:23], v[22:23], v[142:143]
	v_pk_mul_f32 v[24:25], v[24:25], v[144:145]
	v_pk_mul_f32 v[26:27], v[26:27], v[30:31]
	v_pk_mul_f32 v[28:29], v[28:29], v[32:33]
	v_pk_mul_f32 v[18:19], v[18:19], v[22:23]
	v_pk_mul_f32 v[20:21], v[20:21], v[24:25]
	v_cvt_pk_bf16_f32 v26, v26, v27
	v_cvt_pk_bf16_f32 v27, v28, v29
	v_cvt_pk_bf16_f32 v28, v18, v19
	v_cvt_pk_bf16_f32 v29, v20, v21
	s_nop 1
	v_permlane16_swap_b32_e32 v26, v28
	v_permlane16_swap_b32_e32 v27, v29
	global_store_dwordx4 v[34:35], v[26:29], off
	v_pk_mul_f32 v[138:139], v[14:15], s[100:101]
	v_pk_mul_f32 v[140:141], v[16:17], s[100:101]
	v_pk_mul_f32 v[142:143], v[6:7], s[100:101]
	v_pk_mul_f32 v[144:145], v[8:9], s[100:101]
	v_exp_f32_e32 v138, v138
	v_exp_f32_e32 v139, v139
	v_exp_f32_e32 v140, v140
	v_exp_f32_e32 v141, v141
	v_exp_f32_e32 v142, v142
	v_exp_f32_e32 v143, v143
	v_exp_f32_e32 v144, v144
	v_exp_f32_e32 v145, v145
	v_pk_add_f32 v[138:139], v[138:139], 1.0 op_sel_hi:[1,0]
	v_pk_add_f32 v[140:141], v[140:141], 1.0 op_sel_hi:[1,0]
	v_pk_add_f32 v[142:143], v[142:143], 1.0 op_sel_hi:[1,0]
	v_pk_add_f32 v[144:145], v[144:145], 1.0 op_sel_hi:[1,0]
	v_rcp_f32_e32 v138, v138
	v_rcp_f32_e32 v139, v139
	v_rcp_f32_e32 v140, v140
	v_rcp_f32_e32 v141, v141
	v_rcp_f32_e32 v142, v142
	v_rcp_f32_e32 v143, v143
	v_rcp_f32_e32 v144, v144
	v_rcp_f32_e32 v145, v145
	v_pk_mul_f32 v[14:15], v[14:15], v[138:139]
	v_pk_mul_f32 v[16:17], v[16:17], v[140:141]
	v_pk_mul_f32 v[6:7], v[6:7], v[142:143]
	v_pk_mul_f32 v[8:9], v[8:9], v[144:145]
	v_pk_mul_f32 v[10:11], v[10:11], v[14:15]
	v_pk_mul_f32 v[12:13], v[12:13], v[16:17]
	v_pk_mul_f32 v[2:3], v[2:3], v[6:7]
	v_pk_mul_f32 v[4:5], v[4:5], v[8:9]
	v_cvt_pk_bf16_f32 v10, v10, v11
	v_cvt_pk_bf16_f32 v11, v12, v13
	v_cvt_pk_bf16_f32 v12, v2, v3
	v_cvt_pk_bf16_f32 v13, v4, v5
	s_nop 1
	v_permlane16_swap_b32_e32 v10, v12
	v_permlane16_swap_b32_e32 v11, v13
	global_store_dwordx4 v[34:35], v[10:13], off offset:128
	s_cbranch_vccnz .LBB0_1948
	s_andn2_b64 vcc, exec, s[2:3]
	s_cbranch_vccnz .LBB0_1947
	s_barrier
	s_branch .LBB0_1947
